# radix pass 0 wave scans use DPP prefix sums instead of ds_bpermute chains
# baseline (speedup 1.0000x reference)
.LBB0_723:
	s_cmp_lt_i32 s53, 4
	s_cselect_b64 s[14:15], -1, 0
	s_cmp_gt_i32 s53, 3
	v_cmp_ne_u32_e64 s[6:7], 63, v145
	v_cmp_gt_u32_e32 vcc, 32, v145
	s_waitcnt lgkmcnt(0)
	s_barrier
	s_cbranch_scc1 .LBB0_729
	s_lshl_b32 s10, s53, 12
	s_add_i32 s10, s10, 0
	v_lshl_add_u32 v1, v145, 6, s10
	v_add_u32_e32 v1, 0x20000, v1
	ds_read_b128 v[4:7], v1
	ds_read_b128 v[8:11], v1 offset:16
	ds_read_b128 v[12:15], v1 offset:32
	ds_read_b128 v[16:19], v1 offset:48
	s_waitcnt lgkmcnt(3)
	v_add3_u32 v1, v4, v5, v6
	s_waitcnt lgkmcnt(2)
	v_add3_u32 v1, v1, v7, v8
	v_add3_u32 v3, v9, v10, v11
	s_waitcnt lgkmcnt(1)
	v_add3_u32 v1, v1, v12, v13
	v_add3_u32 v3, v3, v14, v15
	s_waitcnt lgkmcnt(0)
	v_add3_u32 v1, v1, v16, v17
	v_add3_u32 v3, v3, v18, v19
	v_and_b32_e32 v5, 63, v147
	v_add_u32_e32 v1, v1, v3
	v_cmp_ne_u32_e64 s[10:11], 63, v5
	v_add_u32_sdwa v8, v1, v1 dst_sel:DWORD dst_unused:UNUSED_PAD src0_sel:WORD_1 src1_sel:WORD_0
	s_lshl_b32 s6, s53, 5
	s_add_i32 s12, s6, 0
	s_add_i32 s6, s12, 0x25804
	v_mov_b32_e32 v5, s6
	ds_read_b32 v5, v5
	v_mov_b32_e32 v9, v8
	s_nop 1
	v_add_u32_dpp v9, v9, v9 row_shr:1 row_mask:0xf bank_mask:0xf
	s_nop 1
	v_add_u32_dpp v9, v9, v9 row_shr:2 row_mask:0xf bank_mask:0xf
	s_nop 1
	v_add_u32_dpp v9, v9, v9 row_shr:4 row_mask:0xf bank_mask:0xf
	s_nop 1
	v_add_u32_dpp v9, v9, v9 row_shr:8 row_mask:0xf bank_mask:0xf
	s_nop 1
	v_add_u32_dpp v9, v9, v9 row_bcast:15 row_mask:0xa bank_mask:0xf
	s_nop 1
	v_add_u32_dpp v9, v9, v9 row_bcast:31 row_mask:0xc bank_mask:0xf
	s_nop 1
	v_readlane_b32 s17, v9, 63
	s_nop 1
	v_sub_u32_e32 v10, s17, v9
	v_add_u32_e32 v9, v10, v8
	s_waitcnt lgkmcnt(0)
	v_cmp_lt_u32_e64 s[6:7], v10, v5
	v_cmp_le_u32_e64 s[10:11], v5, v9
	s_nop 0
	s_and_b64 s[6:7], s[10:11], s[6:7]
	s_ff1_i32_b64 s10, s[6:7]
	s_cmp_lg_u64 s[6:7], 0
	s_cselect_b32 s16, s10, 0
	s_nop 0
	v_readlane_b32 s19, v10, s16
	v_cmp_lt_u32_e64 s[6:7], 31, v145
	v_mov_b32_e32 v8, 0
	s_and_saveexec_b64 s[10:11], vcc
	s_cbranch_execz .LBB0_726
	s_lshl_b32 s17, s53, 10
	s_lshl_b32 s18, s16, 6
	s_add_i32 s18, s18, 0
	s_lshl_b32 s17, s17, 2
	v_lshlrev_b32_e32 v8, 1, v145
	s_add_i32 s18, s18, s17
	v_and_b32_e32 v8, 0x7c, v8
	v_add_u32_e32 v8, s18, v8
	v_add_u32_e32 v8, 0x20000, v8
	ds_read_b32 v8, v8
	v_and_b32_e32 v10, 1, v144
	v_cmp_eq_u32_e32 vcc, 0, v10
	s_waitcnt lgkmcnt(0)
	s_nop 0
	v_cndmask_b32_sdwa v8, v8, v8, vcc dst_sel:DWORD dst_unused:UNUSED_PAD src0_sel:WORD_1 src1_sel:WORD_0
.LBB0_726:
	s_or_b64 exec, exec, s[10:11]
	v_mov_b32_e32 v1, v8
	s_nop 1
	v_add_u32_dpp v1, v1, v1 row_shr:1 row_mask:0xf bank_mask:0xf
	s_nop 1
	v_add_u32_dpp v1, v1, v1 row_shr:2 row_mask:0xf bank_mask:0xf
	s_nop 1
	v_add_u32_dpp v1, v1, v1 row_shr:4 row_mask:0xf bank_mask:0xf
	s_nop 1
	v_add_u32_dpp v1, v1, v1 row_shr:8 row_mask:0xf bank_mask:0xf
	s_nop 1
	v_add_u32_dpp v1, v1, v1 row_bcast:15 row_mask:0xa bank_mask:0xf
	s_nop 1
	v_add_u32_dpp v1, v1, v1 row_bcast:31 row_mask:0xc bank_mask:0xf
	s_nop 1
	v_readlane_b32 s17, v1, 63
	s_nop 3
	s_add_i32 s17, s17, s19
	v_sub_u32_e32 v1, s17, v1
	v_add_u32_e32 v9, v1, v8
	v_cmp_le_u32_e32 vcc, v5, v1
	v_cmp_gt_u32_e64 s[10:11], v5, v9
	s_nop 0
	s_or_b64 s[10:11], s[10:11], vcc
	s_nor_b64 s[10:11], s[6:7], s[10:11]
	s_and_saveexec_b64 s[6:7], s[10:11]
	s_cbranch_execz .LBB0_728
	s_add_i32 s10, s12, 0x25800
	v_lshl_or_b32 v4, s16, 5, v145
	v_sub_u32_e32 v5, v5, v1
	v_mov_b32_e32 v1, s10
	ds_write_b64 v1, v[4:5]
	ds_write_b32 v1, v8 offset:16

.LBB0_975:
	s_or_b64 exec, exec, s[4:5]
	v_mov_b32_e32 v15, v202
	s_add_u32 s62, s28, 0x14000000
	s_waitcnt lgkmcnt(0)
	s_barrier
	s_nop 0
	s_nop 0
	s_nop 0
	s_nop 0
	s_nop 0
	s_nop 0
	s_nop 0
	s_nop 0
	s_nop 0
	s_nop 0
	s_nop 0
	s_nop 0
	s_nop 0
	s_nop 0
	s_nop 0
	s_nop 0
	s_nop 0
	s_nop 0
	s_addc_u32 s63, s29, 0
	v_readfirstlane_b32 s4, v15
	s_ashr_i32 s4, s4, 6
	s_and_b64 s[6:7], s[46:47], exec
	s_cselect_b32 s5, 8, 1
	v_cvt_f32_ubyte0_e32 v1, s5
	v_rcp_iflag_f32_e32 v1, v1
	s_add_i32 s8, s5, -1
	s_and_b64 s[6:7], s[46:47], exec
	s_cselect_b32 s24, 3, 0
	v_mul_f32_e32 v1, 0x4f7ffffe, v1
	v_cvt_u32_f32_e32 v1, v1
	s_sub_i32 s9, 0, s5
	s_abs_i32 s7, s30
	s_lshr_b32 s6, s2, s24
	v_readfirstlane_b32 s10, v1
	s_mul_i32 s9, s9, s10
	s_mul_hi_u32 s9, s10, s9
	s_add_i32 s10, s10, s9
	s_mul_hi_u32 s9, s7, s10
	s_mul_i32 s10, s9, s5
	s_sub_i32 s7, s7, s10
	s_lshl_b32 s6, s6, 3
	s_ashr_i32 s68, s30, 31
	s_add_i32 s10, s9, 1
	s_sub_i32 s11, s7, s5
	s_cmp_ge_u32 s7, s5
	s_cselect_b32 s9, s10, s9
	s_cselect_b32 s7, s11, s7
	s_add_i32 s10, s9, 1
	s_cmp_ge_u32 s7, s5
	s_cselect_b32 s7, s10, s9
	s_xor_b32 s7, s7, s68
	s_sub_i32 s7, s7, s68
	s_lshl_b32 s25, s7, 3
	s_abs_i32 s7, s25
	v_cvt_f32_u32_e32 v1, s7
	s_add_i32 s40, s4, s6
	s_sub_i32 s6, s25, s40
	s_and_b32 s41, s8, s2
	v_rcp_iflag_f32_e32 v1, v1
	s_add_i32 s8, s6, 0x1fff
	s_sub_i32 s6, 0xffffe001, s6
	s_xor_b32 s9, s8, s25
	v_mul_f32_e32 v1, 0x4f7ffffe, v1
	v_cvt_u32_f32_e32 v1, v1
	s_max_i32 s6, s8, s6
	s_sub_i32 s8, 0, s7
	s_ashr_i32 s9, s9, 31
	v_readfirstlane_b32 s10, v1
	s_mul_i32 s8, s8, s10
	s_mul_hi_u32 s8, s10, s8
	s_add_i32 s10, s10, s8
	s_mul_hi_u32 s8, s6, s10
	s_mul_i32 s10, s8, s7
	s_sub_i32 s6, s6, s10
	s_add_i32 s10, s8, 1
	s_sub_i32 s11, s6, s7
	s_cmp_ge_u32 s6, s7
	s_cselect_b32 s8, s10, s8
	s_cselect_b32 s6, s11, s6
	s_add_i32 s10, s8, 1
	s_cmp_ge_u32 s6, s7
	s_cselect_b32 s6, s10, s8
	s_sub_i32 s5, s5, s41
	s_xor_b32 s6, s6, s9
	s_add_i32 s5, s5, 15
	s_sub_i32 s42, s6, s9
	s_lshr_b32 s5, s5, s24
	s_mul_i32 s43, s42, s5
	s_cmp_lt_i32 s43, 1
	s_mov_b32 s9, 0
	s_cbranch_scc1 .LBB0_980
	s_lshl_b32 s5, s4, 14
	s_lshl_b32 s4, s4, 10
	s_add_i32 s47, s4, 0
	s_lshr_b32 s8, s41, 2
	s_add_i32 s46, s5, 0
	s_add_i32 s47, s47, 0x20000
	s_and_b32 s10, s41, 3
	s_lshl_b64 s[4:5], s[8:9], 13
	s_ashr_i32 s6, s40, 31
	s_add_u32 s4, s4, s40
	s_addc_u32 s5, s5, s6
	s_lshl_b64 s[6:7], s[4:5], 9
	v_and_b32_e32 v14, 63, v15
	s_add_u32 s6, s44, s6
	s_addc_u32 s7, s45, s7
	v_lshlrev_b32_e32 v42, 3, v14
	global_load_dwordx2 v[2:3], v42, s[6:7]
	v_and_b32_e32 v17, 15, v15
	v_bfe_u32 v4, v15, 4, 2
	v_bfe_u32 v6, v15, 2, 2
	v_and_b32_e32 v1, 7, v15
	v_lshlrev_b32_e32 v34, 3, v15
	v_mov_b32_e32 v7, 0x1000
	v_lshrrev_b32_e32 v9, 3, v15
	v_or_b32_e32 v12, 16, v17
	v_lshl_or_b32 v6, v4, 2, v6
	v_bfe_u32 v5, v15, 3, 1
	v_and_b32_e32 v10, 1, v15
	v_bitop3_b32 v13, v4, v1, 4 bitop3:0x36
	v_bitop3_b32 v16, v4, v15, 7 bitop3:0x78
	v_and_or_b32 v7, v34, 24, v7
	v_xor_b32_e32 v9, v9, v15
	v_mul_u32_u24_e32 v21, 0x40004, v14
	v_lshrrev_b32_e32 v22, 3, v12
	v_lshlrev_b32_e32 v24, 4, v6
	v_lshlrev_b32_e32 v6, 7, v6
	s_cmpk_gt_i32 s40, 0xff
	s_movk_i32 s6, 0x60
	v_lshlrev_b32_e32 v12, 7, v12
	v_xor_b32_e32 v23, v13, v5
	v_xor_b32_e32 v5, v16, v5
	v_and_or_b32 v9, v9, 6, v10
	v_or_b32_e32 v60, 0x10000, v21
	v_or_b32_e32 v61, 0x30002, v21
	v_xor_b32_e32 v10, v13, v22
	v_xor_b32_e32 v13, v16, v22
	v_or_b32_e32 v16, 0x800, v6
	v_or_b32_e32 v6, v6, v7
	s_cselect_b64 vcc, -1, 0
	v_lshlrev_b32_e32 v11, 6, v15
	s_waitcnt vmcnt(2)
	v_lshlrev_b32_e32 v52, 4, v9
	v_add_u32_e32 v9, s47, v42
	v_lshl_or_b32 v37, v10, 4, v12
	v_bitop3_b32 v10, v24, v16, s6 bitop3:0xce
	v_bitop3_b32 v39, v24, v6, s6 bitop3:0xce
	s_mul_hi_u32 s6, s4, 0x1200
	s_mulk_i32 s5, 0x1200
	s_mulk_i32 s4, 0x1200
	s_add_i32 s6, s6, s5
	v_mov_b32_e32 v43, 0
	s_add_u32 s4, s38, s4
	v_mov_b32_e32 v8, 0x60
	v_lshlrev_b32_e32 v19, 7, v17
	s_addc_u32 s5, s39, s6
	v_lshl_or_b32 v35, v23, 4, v19
	v_lshl_or_b32 v36, v5, 4, v19
	v_and_b32_e32 v5, 0x60, v24
	v_bitop3_b32 v19, v24, 64, v8 bitop3:0x6c
	v_bitop3_b32 v8, v24, 32, v8 bitop3:0x6c
	v_bfe_u32 v18, v15, 3, 3
	v_lshl_or_b32 v38, v13, 4, v12
	v_or_b32_e32 v12, v19, v16
	v_or_b32_e32 v13, v8, v16
	v_or_b32_e32 v41, v8, v6
	v_or_b32_e32 v8, v5, v16
	s_waitcnt vmcnt(1)
	v_or_b32_e32 v56, v6, v5
	v_lshlrev_b32_e32 v16, 3, v4
	v_and_b32_e32 v4, 48, v15
	v_mov_b32_e32 v5, v43
	v_lshlrev_b32_e32 v63, 6, v18
	v_bitop3_b32 v20, v18, v15, 7 bitop3:0x78
	v_or_b32_e32 v40, v19, v6
	v_add_u32_e32 v57, v10, v7
	v_add_u32_e32 v58, v12, v7
	v_add_u32_e32 v59, v13, v7
	v_add_u32_e32 v90, v8, v7
	v_add_u32_e32 v18, s47, v63
	v_mov_b32_e32 v19, v43
	v_lshlrev_b32_e32 v44, 4, v20
	v_mov_b32_e32 v45, v43
	s_mov_b32 m0, s46
	v_mov_b32_e32 v53, v43
	v_mov_b32_e32 v64, 9
	v_xor_b32_e32 v50, 16, v44
	v_mov_b32_e32 v51, v43
	v_xor_b32_e32 v48, 32, v44
	s_waitcnt vmcnt(0)
	v_cndmask_b32_e32 v2, v60, v2, vcc
	v_cndmask_b32_e32 v3, v61, v3, vcc
	ds_write_b64 v9, v[2:3]
	v_and_b32_e32 v2, 0xc0, v11
	v_lshlrev_b32_e32 v62, 1, v2
	v_lshl_or_b32 v2, s10, 9, v62
	v_mov_b32_e32 v3, v43
	v_lshl_add_u64 v[2:3], s[4:5], 0, v[2:3]
	s_lshl_b64 s[4:5], s[8:9], 22
	s_add_u32 s6, s80, s4
	v_lshl_add_u64 v[2:3], v[2:3], 0, v[4:5]
	s_addc_u32 s7, s81, s5
	global_load_dwordx4 v[10:13], v[2:3], off
	global_load_dwordx4 v[6:9], v[2:3], off offset:64
	s_waitcnt lgkmcnt(0)
	s_add_u32 s4, s37, s4
	ds_read_b128 v[30:33], v18
	ds_read_b128 v[22:25], v18 offset:16
	ds_read_b128 v[2:5], v18 offset:32
	ds_read_b128 v[26:29], v18 offset:48
	s_addc_u32 s5, s79, s5
	s_lshl_b32 s8, s10, 7
	s_add_u32 s4, s4, s8
	s_addc_u32 s5, s5, 0
	s_waitcnt lgkmcnt(3)
	v_lshlrev_b32_e32 v18, 9, v30
	s_add_u32 s6, s6, s8
	v_and_b32_e32 v18, 0x1fffe00, v18
	s_addc_u32 s7, s7, 0
	v_lshl_add_u64 v[20:21], s[4:5], 0, v[18:19]
	s_add_i32 s48, s46, 0x1000
	v_lshl_add_u64 v[20:21], v[20:21], 0, v[44:45]
	v_lshl_add_u64 v[18:19], s[6:7], 0, v[18:19]
	global_load_lds_dwordx4 v[20:21], off
	v_lshl_add_u64 v[18:19], v[18:19], 0, v[52:53]
	s_mov_b32 m0, s48
	s_add_i32 s49, s46, 0x400
	global_load_lds_dwordx4 v[18:19], off
	v_lshlrev_b32_sdwa v18, v64, v30 dst_sel:DWORD dst_unused:UNUSED_PAD src0_sel:DWORD src1_sel:WORD_1
	v_mov_b32_e32 v19, v43
	v_lshl_add_u64 v[20:21], s[4:5], 0, v[18:19]
	v_lshl_add_u64 v[20:21], v[20:21], 0, v[50:51]
	s_mov_b32 m0, s49
	v_lshl_add_u64 v[18:19], s[6:7], 0, v[18:19]
	s_add_i32 s50, s46, 0x1400
	global_load_lds_dwordx4 v[20:21], off
	v_lshl_add_u64 v[18:19], v[18:19], 0, v[52:53]
	s_mov_b32 m0, s50
	v_mov_b32_e32 v49, v43
	global_load_lds_dwordx4 v[18:19], off
	v_lshlrev_b32_e32 v18, 9, v31
	v_and_b32_e32 v18, 0x1fffe00, v18
	v_mov_b32_e32 v19, v43
	v_lshl_add_u64 v[20:21], s[4:5], 0, v[18:19]
	s_add_i32 s51, s46, 0x800
	v_lshl_add_u64 v[20:21], v[20:21], 0, v[48:49]
	s_mov_b32 m0, s51
	v_lshl_add_u64 v[18:19], s[6:7], 0, v[18:19]
	s_add_i32 s52, s46, 0x1800
	global_load_lds_dwordx4 v[20:21], off
	v_lshl_add_u64 v[18:19], v[18:19], 0, v[52:53]
	s_mov_b32 m0, s52
	v_xor_b32_e32 v46, 48, v44
	global_load_lds_dwordx4 v[18:19], off
	v_lshlrev_b32_sdwa v18, v64, v31 dst_sel:DWORD dst_unused:UNUSED_PAD src0_sel:DWORD src1_sel:WORD_1
	v_mov_b32_e32 v19, v43
	v_lshl_add_u64 v[20:21], s[4:5], 0, v[18:19]
	v_mov_b32_e32 v47, v43
	s_add_i32 s53, s46, 0xc00
	v_lshl_add_u64 v[20:21], v[20:21], 0, v[46:47]
	s_mov_b32 m0, s53
	v_lshl_add_u64 v[18:19], s[6:7], 0, v[18:19]
	s_add_i32 s54, s46, 0x1c00
	global_load_lds_dwordx4 v[20:21], off
	v_lshl_add_u64 v[18:19], v[18:19], 0, v[52:53]
	s_mov_b32 m0, s54
	v_cmp_gt_u32_e64 s[4:5], 4, v17
	global_load_lds_dwordx4 v[18:19], off
	v_and_b32_e32 v17, 0x80, v34
	v_bfe_u32 v15, v15, 5, 1
	v_or_b32_e32 v19, 32, v17
	v_or_b32_e32 v20, 64, v17
	v_or_b32_e32 v21, 0x60, v17
	v_or_b32_e32 v30, 6, v15
	v_or_b32_e32 v82, v17, v30
	v_or_b32_e32 v84, v19, v30
	v_or_b32_e32 v86, v20, v30
	v_or_b32_e32 v88, v21, v30
	v_or_b32_e32 v30, 10, v15
	v_or_b32_e32 v18, 2, v15
	v_or_b32_e32 v98, v17, v30
	v_or_b32_e32 v100, v19, v30
	v_or_b32_e32 v102, v20, v30
	v_or_b32_e32 v104, v21, v30
	v_or_b32_e32 v30, 14, v15
	v_or_b32_e32 v66, v17, v18
	v_or_b32_e32 v68, v19, v18
	v_or_b32_e32 v70, v20, v18
	v_or_b32_e32 v72, v21, v18
	v_or_b32_e32 v18, 4, v15
	v_or_b32_e32 v106, v17, v30
	v_or_b32_e32 v108, v19, v30
	v_or_b32_e32 v110, v20, v30
	v_or_b32_e32 v112, v21, v30
	v_or_b32_e32 v30, 18, v15
	v_or_b32_e32 v81, v17, v18
	v_or_b32_e32 v83, v19, v18
	v_or_b32_e32 v85, v20, v18
	v_or_b32_e32 v87, v21, v18
	v_or_b32_e32 v18, 8, v15
	v_or_b32_e32 v114, v17, v30
	v_or_b32_e32 v116, v19, v30
	v_or_b32_e32 v118, v20, v30
	v_or_b32_e32 v120, v21, v30
	v_or_b32_e32 v30, 22, v15
	v_lshl_add_u64 v[54:55], s[44:45], 0, v[42:43]
	v_or_b32_e32 v97, v17, v18
	v_or_b32_e32 v99, v19, v18
	v_or_b32_e32 v101, v20, v18
	v_or_b32_e32 v103, v21, v18
	v_or_b32_e32 v18, 12, v15
	v_or_b32_e32 v122, v17, v30
	v_or_b32_e32 v124, v19, v30
	v_or_b32_e32 v126, v20, v30
	v_or_b32_e32 v128, v21, v30
	v_or_b32_e32 v30, 26, v15
	s_abs_i32 s45, s42
	v_or_b32_e32 v105, v17, v18
	v_or_b32_e32 v107, v19, v18
	v_or_b32_e32 v109, v20, v18
	v_or_b32_e32 v111, v21, v18
	v_or_b32_e32 v18, 16, v15
	v_or_b32_e32 v130, v17, v30
	v_or_b32_e32 v132, v19, v30
	v_or_b32_e32 v134, v20, v30
	v_or_b32_e32 v136, v21, v30
	v_cvt_f32_u32_e32 v30, s45
	v_or_b32_e32 v113, v17, v18
	v_or_b32_e32 v115, v19, v18
	v_or_b32_e32 v117, v20, v18
	v_or_b32_e32 v119, v21, v18
	v_or_b32_e32 v18, 20, v15
	v_or_b32_e32 v121, v17, v18
	v_or_b32_e32 v123, v19, v18
	v_or_b32_e32 v125, v20, v18
	v_or_b32_e32 v127, v21, v18
	v_or_b32_e32 v18, 24, v15
	v_or_b32_e32 v65, v17, v15
	v_or_b32_e32 v67, v19, v15
	v_or_b32_e32 v69, v20, v15
	v_or_b32_e32 v71, v21, v15
	v_or_b32_e32 v129, v17, v18
	v_or_b32_e32 v131, v19, v18
	v_or_b32_e32 v133, v20, v18
	v_or_b32_e32 v135, v21, v18
	v_or_b32_e32 v18, 28, v15
	v_or_b32_e32 v15, 30, v15
	v_or_b32_e32 v137, v17, v18
	v_or_b32_e32 v138, v17, v15
	v_rcp_iflag_f32_e32 v17, v30
	s_sub_i32 s8, 0, s45
	s_add_i32 s44, s46, 0x2000
	v_lshlrev_b32_e32 v1, 2, v14
	v_mul_f32_e32 v17, 0x4f7ffffe, v17
	v_cvt_u32_f32_e32 v17, v17
	s_waitcnt vmcnt(0)
	v_cndmask_b32_e64 v9, 0, v9, s[4:5]
	v_cndmask_b32_e64 v8, 0, v8, s[4:5]
	v_cndmask_b32_e64 v7, 0, v7, s[4:5]
	v_readfirstlane_b32 s10, v17
	s_mul_i32 s8, s8, s10
	s_mul_hi_u32 s8, s10, s8
	v_cndmask_b32_e64 v6, 0, v6, s[4:5]
	v_cndmask_b32_e64 v13, 0, v13, s[4:5]
	v_cndmask_b32_e64 v12, 0, v12, s[4:5]
	v_cndmask_b32_e64 v11, 0, v11, s[4:5]
	v_cndmask_b32_e64 v10, 0, v10, s[4:5]
	v_cmp_gt_u32_e64 s[6:7], 16, v14
	v_add_u32_e32 v73, s46, v56
	v_add_u32_e32 v74, s46, v90
	v_add_u32_e32 v75, s46, v41
	v_add_u32_e32 v76, s46, v59
	v_add_u32_e32 v77, s46, v40
	v_add_u32_e32 v78, s46, v58
	v_add_u32_e32 v79, s46, v39
	v_add_u32_e32 v80, s46, v57
	v_add_u32_e32 v89, s44, v56
	v_add_u32_e32 v90, s44, v90
	v_add_u32_e32 v91, s44, v41
	v_add_u32_e32 v92, s44, v59
	v_add_u32_e32 v93, s44, v40
	v_add_u32_e32 v94, s44, v58
	v_add_u32_e32 v95, s44, v39
	v_add_u32_e32 v96, s44, v57
	v_or_b32_e32 v139, v19, v18
	v_or_b32_e32 v140, v19, v15
	v_or_b32_e32 v141, v20, v18
	v_or_b32_e32 v142, v20, v15
	v_or_b32_e32 v143, v21, v18
	v_or_b32_e32 v144, v21, v15
	s_ashr_i32 s55, s42, 31
	s_add_i32 s56, s10, s8
	s_sub_i32 s57, 0, s42
	v_lshlrev_b32_e32 v56, 1, v16
	s_add_i32 s58, s46, 0x3000
	s_add_i32 s59, s46, 0x2400
	s_add_i32 s60, s46, 0x3400
	s_add_i32 s61, s46, 0x2800
	s_add_i32 s64, s46, 0x3800
	s_add_i32 s65, s46, 0x2c00
	s_add_i32 s66, s46, 0x3c00
	v_add_u32_e32 v145, s46, v36
	v_add_u32_e32 v149, s46, v35
	v_add_u32_e32 v151, s46, v38
	v_add_u32_e32 v153, s46, v37
	v_lshlrev_b32_e32 v58, 1, v14
	s_movk_i32 s67, 0x7fff
	s_mov_b32 s69, 0
	s_mov_b32 s70, 0
	s_branch .LBB0_978
